# adds: NSA1 q/gate prefetch, late weight conversion shared by workgroups 32..255, NSA1 selection arg-max on registers
# baseline (speedup 1.0000x reference)
.LBB0_544:
	s_waitcnt vmcnt(0)
	v_ashrrev_i32_e32 v1, 6, v94
	v_cmp_lt_i32_e32 vcc, 15, v1
	s_barrier
	s_and_saveexec_b64 s[0:1], vcc
	s_xor_b64 s[20:21], exec, s[0:1]
	s_cbranch_execz .LBB0_551
	v_lshlrev_b32_e64 v0, v1, 1
	v_add_u32_e32 v1, -1, v1
	v_lshlrev_b32_e64 v2, v1, 1
	v_bfm_b32 v1, v1, 0
	v_or3_b32 v0, v0, v2, 1
	v_and_b32_e32 v1, -2, v1
	v_add_u32_e32 v2, s74, v95
	s_mov_b32 s0, 0
	ds_read_b32 v16, v2 offset:0
	ds_read_b32 v17, v2 offset:4
	ds_read_b32 v18, v2 offset:8
	ds_read_b32 v19, v2 offset:12
	ds_read_b32 v20, v2 offset:16
	ds_read_b32 v21, v2 offset:20
	ds_read_b32 v22, v2 offset:24
	ds_read_b32 v23, v2 offset:28
	ds_read_b32 v24, v2 offset:32
	ds_read_b32 v25, v2 offset:36
	ds_read_b32 v26, v2 offset:40
	ds_read_b32 v27, v2 offset:44
	ds_read_b32 v28, v2 offset:48
	ds_read_b32 v29, v2 offset:52
	ds_read_b32 v30, v2 offset:56
	ds_read_b32 v31, v2 offset:60
	ds_read_b32 v32, v2 offset:64
	ds_read_b32 v33, v2 offset:68
	ds_read_b32 v34, v2 offset:72
	ds_read_b32 v35, v2 offset:76
	ds_read_b32 v36, v2 offset:80
	ds_read_b32 v37, v2 offset:84
	ds_read_b32 v38, v2 offset:88
	ds_read_b32 v39, v2 offset:92
	ds_read_b32 v40, v2 offset:96
	ds_read_b32 v41, v2 offset:100
	ds_read_b32 v42, v2 offset:104
	ds_read_b32 v43, v2 offset:108
	ds_read_b32 v44, v2 offset:112
	s_waitcnt lgkmcnt(0)
.Lnsa1_sel_round:
	v_mov_b32_e32 v4, 0xff61b1e6
	v_mov_b32_e32 v3, 0
	v_and_b32_e32 v7, 0x2, v1
	v_cmp_gt_f32_e64 s[4:5], v16, v4
	v_cmp_ne_u32_e32 vcc, 0, v7
	s_nop 0
	s_and_b64 vcc, vcc, s[4:5]
	s_nop 0
	v_cndmask_b32_e32 v4, v4, v16, vcc
	v_cndmask_b32_e64 v3, v3, 1, vcc
	v_and_b32_e32 v7, 0x4, v1
	v_cmp_gt_f32_e64 s[4:5], v17, v4
	v_cmp_ne_u32_e32 vcc, 0, v7
	s_nop 0
	s_and_b64 vcc, vcc, s[4:5]
	s_nop 0
	v_cndmask_b32_e32 v4, v4, v17, vcc
	v_cndmask_b32_e64 v3, v3, 2, vcc
	v_and_b32_e32 v7, 0x8, v1
	v_cmp_gt_f32_e64 s[4:5], v18, v4
	v_cmp_ne_u32_e32 vcc, 0, v7
	s_nop 0
	s_and_b64 vcc, vcc, s[4:5]
	s_nop 0
	v_cndmask_b32_e32 v4, v4, v18, vcc
	v_cndmask_b32_e64 v3, v3, 3, vcc
	v_and_b32_e32 v7, 0x10, v1
	v_cmp_gt_f32_e64 s[4:5], v19, v4
	v_cmp_ne_u32_e32 vcc, 0, v7
	s_nop 0
	s_and_b64 vcc, vcc, s[4:5]
	s_nop 0
	v_cndmask_b32_e32 v4, v4, v19, vcc
	v_cndmask_b32_e64 v3, v3, 4, vcc
	v_and_b32_e32 v7, 0x20, v1
	v_cmp_gt_f32_e64 s[4:5], v20, v4
	v_cmp_ne_u32_e32 vcc, 0, v7
	s_nop 0
	s_and_b64 vcc, vcc, s[4:5]
	s_nop 0
	v_cndmask_b32_e32 v4, v4, v20, vcc
	v_cndmask_b32_e64 v3, v3, 5, vcc
	v_and_b32_e32 v7, 0x40, v1
	v_cmp_gt_f32_e64 s[4:5], v21, v4
	v_cmp_ne_u32_e32 vcc, 0, v7
	s_nop 0
	s_and_b64 vcc, vcc, s[4:5]
	s_nop 0
	v_cndmask_b32_e32 v4, v4, v21, vcc
	v_cndmask_b32_e64 v3, v3, 6, vcc
	v_and_b32_e32 v7, 0x80, v1
	v_cmp_gt_f32_e64 s[4:5], v22, v4
	v_cmp_ne_u32_e32 vcc, 0, v7
	s_nop 0
	s_and_b64 vcc, vcc, s[4:5]
	s_nop 0
	v_cndmask_b32_e32 v4, v4, v22, vcc
	v_cndmask_b32_e64 v3, v3, 7, vcc
	v_and_b32_e32 v7, 0x100, v1
	v_cmp_gt_f32_e64 s[4:5], v23, v4
	v_cmp_ne_u32_e32 vcc, 0, v7
	s_nop 0
	s_and_b64 vcc, vcc, s[4:5]
	s_nop 0
	v_cndmask_b32_e32 v4, v4, v23, vcc
	v_cndmask_b32_e64 v3, v3, 8, vcc
	v_and_b32_e32 v7, 0x200, v1
	v_cmp_gt_f32_e64 s[4:5], v24, v4
	v_cmp_ne_u32_e32 vcc, 0, v7
	s_nop 0
	s_and_b64 vcc, vcc, s[4:5]
	s_nop 0
	v_cndmask_b32_e32 v4, v4, v24, vcc
	v_cndmask_b32_e64 v3, v3, 9, vcc
	v_and_b32_e32 v7, 0x400, v1
	v_cmp_gt_f32_e64 s[4:5], v25, v4
	v_cmp_ne_u32_e32 vcc, 0, v7
	s_nop 0
	s_and_b64 vcc, vcc, s[4:5]
	s_nop 0
	v_cndmask_b32_e32 v4, v4, v25, vcc
	v_cndmask_b32_e64 v3, v3, 10, vcc
	v_and_b32_e32 v7, 0x800, v1
	v_cmp_gt_f32_e64 s[4:5], v26, v4
	v_cmp_ne_u32_e32 vcc, 0, v7
	s_nop 0
	s_and_b64 vcc, vcc, s[4:5]
	s_nop 0
	v_cndmask_b32_e32 v4, v4, v26, vcc
	v_cndmask_b32_e64 v3, v3, 11, vcc
	v_and_b32_e32 v7, 0x1000, v1
	v_cmp_gt_f32_e64 s[4:5], v27, v4
	v_cmp_ne_u32_e32 vcc, 0, v7
	s_nop 0
	s_and_b64 vcc, vcc, s[4:5]
	s_nop 0
	v_cndmask_b32_e32 v4, v4, v27, vcc
	v_cndmask_b32_e64 v3, v3, 12, vcc
	v_and_b32_e32 v7, 0x2000, v1
	v_cmp_gt_f32_e64 s[4:5], v28, v4
	v_cmp_ne_u32_e32 vcc, 0, v7
	s_nop 0
	s_and_b64 vcc, vcc, s[4:5]
	s_nop 0
	v_cndmask_b32_e32 v4, v4, v28, vcc
	v_cndmask_b32_e64 v3, v3, 13, vcc
	v_and_b32_e32 v7, 0x4000, v1
	v_cmp_gt_f32_e64 s[4:5], v29, v4
	v_cmp_ne_u32_e32 vcc, 0, v7
	s_nop 0
	s_and_b64 vcc, vcc, s[4:5]
	s_nop 0
	v_cndmask_b32_e32 v4, v4, v29, vcc
	v_cndmask_b32_e64 v3, v3, 14, vcc
	v_and_b32_e32 v7, 0x8000, v1
	v_cmp_gt_f32_e64 s[4:5], v30, v4
	v_cmp_ne_u32_e32 vcc, 0, v7
	s_nop 0
	s_and_b64 vcc, vcc, s[4:5]
	s_nop 0
	v_cndmask_b32_e32 v4, v4, v30, vcc
	v_cndmask_b32_e64 v3, v3, 15, vcc
	v_and_b32_e32 v7, 0x10000, v1
	v_cmp_gt_f32_e64 s[4:5], v31, v4
	v_cmp_ne_u32_e32 vcc, 0, v7
	s_nop 0
	s_and_b64 vcc, vcc, s[4:5]
	s_nop 0
	v_cndmask_b32_e32 v4, v4, v31, vcc
	v_cndmask_b32_e64 v3, v3, 16, vcc
	v_and_b32_e32 v7, 0x20000, v1
	v_cmp_gt_f32_e64 s[4:5], v32, v4
	v_cmp_ne_u32_e32 vcc, 0, v7
	s_nop 0
	s_and_b64 vcc, vcc, s[4:5]
	s_nop 0
	v_cndmask_b32_e32 v4, v4, v32, vcc
	v_cndmask_b32_e64 v3, v3, 17, vcc
	v_and_b32_e32 v7, 0x40000, v1
	v_cmp_gt_f32_e64 s[4:5], v33, v4
	v_cmp_ne_u32_e32 vcc, 0, v7
	s_nop 0
	s_and_b64 vcc, vcc, s[4:5]
	s_nop 0
	v_cndmask_b32_e32 v4, v4, v33, vcc
	v_cndmask_b32_e64 v3, v3, 18, vcc
	v_and_b32_e32 v7, 0x80000, v1
	v_cmp_gt_f32_e64 s[4:5], v34, v4
	v_cmp_ne_u32_e32 vcc, 0, v7
	s_nop 0
	s_and_b64 vcc, vcc, s[4:5]
	s_nop 0
	v_cndmask_b32_e32 v4, v4, v34, vcc
	v_cndmask_b32_e64 v3, v3, 19, vcc
	v_and_b32_e32 v7, 0x100000, v1
	v_cmp_gt_f32_e64 s[4:5], v35, v4
	v_cmp_ne_u32_e32 vcc, 0, v7
	s_nop 0
	s_and_b64 vcc, vcc, s[4:5]
	s_nop 0
	v_cndmask_b32_e32 v4, v4, v35, vcc
	v_cndmask_b32_e64 v3, v3, 20, vcc
	v_and_b32_e32 v7, 0x200000, v1
	v_cmp_gt_f32_e64 s[4:5], v36, v4
	v_cmp_ne_u32_e32 vcc, 0, v7
	s_nop 0
	s_and_b64 vcc, vcc, s[4:5]
	s_nop 0
	v_cndmask_b32_e32 v4, v4, v36, vcc
	v_cndmask_b32_e64 v3, v3, 21, vcc
	v_and_b32_e32 v7, 0x400000, v1
	v_cmp_gt_f32_e64 s[4:5], v37, v4
	v_cmp_ne_u32_e32 vcc, 0, v7
	s_nop 0
	s_and_b64 vcc, vcc, s[4:5]
	s_nop 0
	v_cndmask_b32_e32 v4, v4, v37, vcc
	v_cndmask_b32_e64 v3, v3, 22, vcc
	v_and_b32_e32 v7, 0x800000, v1
	v_cmp_gt_f32_e64 s[4:5], v38, v4
	v_cmp_ne_u32_e32 vcc, 0, v7
	s_nop 0
	s_and_b64 vcc, vcc, s[4:5]
	s_nop 0
	v_cndmask_b32_e32 v4, v4, v38, vcc
	v_cndmask_b32_e64 v3, v3, 23, vcc
	v_and_b32_e32 v7, 0x1000000, v1
	v_cmp_gt_f32_e64 s[4:5], v39, v4
	v_cmp_ne_u32_e32 vcc, 0, v7
	s_nop 0
	s_and_b64 vcc, vcc, s[4:5]
	s_nop 0
	v_cndmask_b32_e32 v4, v4, v39, vcc
	v_cndmask_b32_e64 v3, v3, 24, vcc
	v_and_b32_e32 v7, 0x2000000, v1
	v_cmp_gt_f32_e64 s[4:5], v40, v4
	v_cmp_ne_u32_e32 vcc, 0, v7
	s_nop 0
	s_and_b64 vcc, vcc, s[4:5]
	s_nop 0
	v_cndmask_b32_e32 v4, v4, v40, vcc
	v_cndmask_b32_e64 v3, v3, 25, vcc
	v_and_b32_e32 v7, 0x4000000, v1
	v_cmp_gt_f32_e64 s[4:5], v41, v4
	v_cmp_ne_u32_e32 vcc, 0, v7
	s_nop 0
	s_and_b64 vcc, vcc, s[4:5]
	s_nop 0
	v_cndmask_b32_e32 v4, v4, v41, vcc
	v_cndmask_b32_e64 v3, v3, 26, vcc
	v_and_b32_e32 v7, 0x8000000, v1
	v_cmp_gt_f32_e64 s[4:5], v42, v4
	v_cmp_ne_u32_e32 vcc, 0, v7
	s_nop 0
	s_and_b64 vcc, vcc, s[4:5]
	s_nop 0
	v_cndmask_b32_e32 v4, v4, v42, vcc
	v_cndmask_b32_e64 v3, v3, 27, vcc
	v_and_b32_e32 v7, 0x10000000, v1
	v_cmp_gt_f32_e64 s[4:5], v43, v4
	v_cmp_ne_u32_e32 vcc, 0, v7
	s_nop 0
	s_and_b64 vcc, vcc, s[4:5]
	s_nop 0
	v_cndmask_b32_e32 v4, v4, v43, vcc
	v_cndmask_b32_e64 v3, v3, 28, vcc
	v_and_b32_e32 v7, 0x20000000, v1
	v_cmp_gt_f32_e64 s[4:5], v44, v4
	v_cmp_ne_u32_e32 vcc, 0, v7
	s_nop 0
	s_and_b64 vcc, vcc, s[4:5]
	s_nop 0
	v_cndmask_b32_e32 v4, v4, v44, vcc
	v_cndmask_b32_e64 v3, v3, 29, vcc
	v_lshlrev_b32_e64 v3, v3, 1
	s_add_i32 s0, s0, 1
	v_or_b32_e32 v0, v3, v0
	s_cmp_eq_u32 s0, 13
	v_bitop3_b32 v1, v1, v3, v1 bitop3:0x30
	s_cbranch_scc0 .Lnsa1_sel_round
	s_andn2_saveexec_b64 s[4:5], s[20:21]
	s_cbranch_execnz .LBB0_552
